# RSTD row table: all units' ssq loads issued together (one wait) instead of one memory latency per unit, in the three RSTD GEMM phases
# speedup vs baseline: 1.0054x; 1.0054x over previous
.LBB0_692:
	v_readlane_b32 s0, v253, 36
	v_readlane_b32 s1, v253, 37
	s_mul_i32 s28, s0, 0xc3000
	s_ashr_i32 s34, s16, 3
	s_lshl_b64 s[0:1], s[28:29], 2
	s_add_u32 s0, s6, s0
	s_addc_u32 s1, s7, s1
	s_add_u32 s16, s0, 0x4385a400
	s_movk_i32 s0, 0x100
	v_readlane_b32 s18, v254, 24
	s_addc_u32 s17, s1, 0
	s_ashr_i32 s25, s24, 31
	v_cmp_gt_i32_e64 s[0:1], s0, v0
	v_lshl_add_u32 v2, v0, 2, s18
	s_mov_b64 s[18:19], s[4:5]
	s_mov_b32 s100, 0
	s_branch .LBB0_695
.LBB0_693:
	s_or_b64 exec, exec, s[20:21]
	s_add_u32 s18, s18, s24
	s_addc_u32 s19, s19, s25
	s_add_i32 s100, s100, 1
	s_mov_b64 s[20:21], 0

.LBB0_701:
	s_ashr_i32 s28, s28, 3
	s_add_i32 s28, s35, s28
	s_mul_hi_i32 s35, s28, 0x2e8ba2e9
	s_lshr_b32 s36, s35, 31
	s_ashr_i32 s35, s35, 5
	s_add_i32 s35, s35, s36
	s_lshl_b32 s36, s35, 3
	s_sub_i32 s37, 0x41, s36
	s_min_i32 s37, s37, 8
	s_abs_i32 s37, s37
	v_cvt_f32_u32_e32 v3, s37
	s_sub_i32 s38, 0, s37
	s_mulk_i32 s35, 0xb0
	s_sub_i32 s28, s28, s35
	v_rcp_iflag_f32_e32 v3, v3
	s_ashr_i32 s35, s28, 31
	s_abs_i32 s28, s28
	v_mul_f32_e32 v3, 0x4f7ffffe, v3
	v_cvt_u32_f32_e32 v3, v3
	s_nop 0
	v_readfirstlane_b32 s39, v3
	s_mul_i32 s38, s38, s39
	s_mul_hi_u32 s38, s39, s38
	s_add_i32 s39, s39, s38
	s_mul_hi_u32 s38, s28, s39
	s_mul_i32 s38, s38, s37
	s_sub_i32 s28, s28, s38
	s_sub_i32 s38, s28, s37
	s_cmp_ge_u32 s28, s37
	s_cselect_b32 s28, s38, s28
	s_sub_i32 s38, s28, s37
	s_cmp_ge_u32 s28, s37
	s_cselect_b32 s28, s38, s28
	s_xor_b32 s28, s28, s35
	s_sub_i32 s28, s28, s35
	s_add_i32 s28, s28, s36
	s_mov_b32 m0, s100
	s_nop 0
	v_writelane_b32 v255, s28, m0
	s_branch .LBB0_693
.LBB0_702:
	s_and_saveexec_b64 vcc, s[0:1]
	s_cbranch_execz .Lrta_end
	s_cmp_lt_u32 0, s100
	s_cbranch_scc0 .Lrta_wait
	v_readlane_b32 s101, v255, 0
	s_nop 0
	v_lshl_add_u32 v4, s101, 8, v0
	v_ashrrev_i32_e32 v5, 31, v4
	v_lshlrev_b64 v[4:5], 6, v[4:5]
	v_lshl_add_u64 v[8:9], s[16:17], 0, v[4:5]
	global_load_dwordx4 v[24:27], v[8:9], off
	global_load_dwordx4 v[28:31], v[8:9], off offset:32
	global_load_dwordx4 v[32:35], v[8:9], off offset:16
	global_load_dwordx4 v[36:39], v[8:9], off offset:48
	s_cmp_lt_u32 1, s100
	s_cbranch_scc0 .Lrta_wait
	v_readlane_b32 s101, v255, 1
	s_nop 0
	v_lshl_add_u32 v4, s101, 8, v0
	v_ashrrev_i32_e32 v5, 31, v4
	v_lshlrev_b64 v[4:5], 6, v[4:5]
	v_lshl_add_u64 v[8:9], s[16:17], 0, v[4:5]
	global_load_dwordx4 v[40:43], v[8:9], off
	global_load_dwordx4 v[44:47], v[8:9], off offset:32
	global_load_dwordx4 v[48:51], v[8:9], off offset:16
	global_load_dwordx4 v[52:55], v[8:9], off offset:48
	s_cmp_lt_u32 2, s100
	s_cbranch_scc0 .Lrta_wait
	v_readlane_b32 s101, v255, 2
	s_nop 0
	v_lshl_add_u32 v4, s101, 8, v0
	v_ashrrev_i32_e32 v5, 31, v4
	v_lshlrev_b64 v[4:5], 6, v[4:5]
	v_lshl_add_u64 v[8:9], s[16:17], 0, v[4:5]
	global_load_dwordx4 v[56:59], v[8:9], off
	global_load_dwordx4 v[60:63], v[8:9], off offset:32
	global_load_dwordx4 v[64:67], v[8:9], off offset:16
	global_load_dwordx4 v[68:71], v[8:9], off offset:48
	s_cmp_lt_u32 3, s100
	s_cbranch_scc0 .Lrta_wait
	v_readlane_b32 s101, v255, 3
	s_nop 0
	v_lshl_add_u32 v4, s101, 8, v0
	v_ashrrev_i32_e32 v5, 31, v4
	v_lshlrev_b64 v[4:5], 6, v[4:5]
	v_lshl_add_u64 v[8:9], s[16:17], 0, v[4:5]
	global_load_dwordx4 v[72:75], v[8:9], off
	global_load_dwordx4 v[76:79], v[8:9], off offset:32
	global_load_dwordx4 v[80:83], v[8:9], off offset:16
	global_load_dwordx4 v[84:87], v[8:9], off offset:48
	s_cmp_lt_u32 4, s100
	s_cbranch_scc0 .Lrta_wait
	v_readlane_b32 s101, v255, 4
	s_nop 0
	v_lshl_add_u32 v4, s101, 8, v0
	v_ashrrev_i32_e32 v5, 31, v4
	v_lshlrev_b64 v[4:5], 6, v[4:5]
	v_lshl_add_u64 v[8:9], s[16:17], 0, v[4:5]
	global_load_dwordx4 v[88:91], v[8:9], off
	global_load_dwordx4 v[92:95], v[8:9], off offset:32
	global_load_dwordx4 v[96:99], v[8:9], off offset:16
	global_load_dwordx4 v[100:103], v[8:9], off offset:48
	s_cmp_lt_u32 5, s100
	s_cbranch_scc0 .Lrta_wait
	v_readlane_b32 s101, v255, 5
	s_nop 0
	v_lshl_add_u32 v4, s101, 8, v0
	v_ashrrev_i32_e32 v5, 31, v4
	v_lshlrev_b64 v[4:5], 6, v[4:5]
	v_lshl_add_u64 v[8:9], s[16:17], 0, v[4:5]
	global_load_dwordx4 v[104:107], v[8:9], off
	global_load_dwordx4 v[108:111], v[8:9], off offset:32
	global_load_dwordx4 v[112:115], v[8:9], off offset:16
	global_load_dwordx4 v[116:119], v[8:9], off offset:48
.Lrta_wait:
	s_waitcnt vmcnt(0)
	s_cmp_lt_u32 0, s100
	s_cbranch_scc0 .Lrta_end
	v_mov_b32_e32 v4, v24
	v_mov_b32_e32 v5, v25
	v_mov_b32_e32 v6, v26
	v_mov_b32_e32 v7, v27
	v_mov_b32_e32 v12, v28
	v_mov_b32_e32 v13, v29
	v_mov_b32_e32 v14, v30
	v_mov_b32_e32 v15, v31
	v_mov_b32_e32 v16, v32
	v_mov_b32_e32 v17, v33
	v_mov_b32_e32 v18, v34
	v_mov_b32_e32 v19, v35
	v_mov_b32_e32 v20, v36
	v_mov_b32_e32 v21, v37
	v_mov_b32_e32 v22, v38
	v_mov_b32_e32 v23, v39
	v_mov_b32_e32 v8, v4
	v_mov_b32_e32 v9, v12
	v_mov_b32_e32 v12, v5
	v_mov_b32_e32 v4, v6
	v_mov_b32_e32 v5, v14
	v_mov_b32_e32 v14, v7
	v_mov_b32_e32 v6, v16
	v_mov_b32_e32 v7, v20
	v_mov_b32_e32 v20, v17
	v_mov_b32_e32 v16, v18
	v_mov_b32_e32 v17, v22
	v_mov_b32_e32 v22, v19
	v_pk_add_f32 v[8:9], v[8:9], v[12:13]
	v_pk_add_f32 v[4:5], v[4:5], v[14:15]
	v_pk_add_f32 v[6:7], v[6:7], v[20:21]
	v_pk_add_f32 v[12:13], v[16:17], v[22:23]
	v_pk_add_f32 v[4:5], v[8:9], v[4:5]
	v_pk_add_f32 v[6:7], v[6:7], v[12:13]
	s_nop 0
	v_pk_add_f32 v[4:5], v[4:5], v[6:7]
	s_nop 0
	v_add_f32_e32 v3, v4, v5
	v_fmamk_f32 v3, v3, 0x3a800000, v231
	v_rsq_f32_e32 v3, v3
	ds_write_b32 v2, v3
	s_cmp_lt_u32 1, s100
	s_cbranch_scc0 .Lrta_end
	v_mov_b32_e32 v4, v40
	v_mov_b32_e32 v5, v41
	v_mov_b32_e32 v6, v42
	v_mov_b32_e32 v7, v43
	v_mov_b32_e32 v12, v44
	v_mov_b32_e32 v13, v45
	v_mov_b32_e32 v14, v46
	v_mov_b32_e32 v15, v47
	v_mov_b32_e32 v16, v48
	v_mov_b32_e32 v17, v49
	v_mov_b32_e32 v18, v50
	v_mov_b32_e32 v19, v51
	v_mov_b32_e32 v20, v52
	v_mov_b32_e32 v21, v53
	v_mov_b32_e32 v22, v54
	v_mov_b32_e32 v23, v55
	v_mov_b32_e32 v8, v4
	v_mov_b32_e32 v9, v12
	v_mov_b32_e32 v12, v5
	v_mov_b32_e32 v4, v6
	v_mov_b32_e32 v5, v14
	v_mov_b32_e32 v14, v7
	v_mov_b32_e32 v6, v16
	v_mov_b32_e32 v7, v20
	v_mov_b32_e32 v20, v17
	v_mov_b32_e32 v16, v18
	v_mov_b32_e32 v17, v22
	v_mov_b32_e32 v22, v19
	v_pk_add_f32 v[8:9], v[8:9], v[12:13]
	v_pk_add_f32 v[4:5], v[4:5], v[14:15]
	v_pk_add_f32 v[6:7], v[6:7], v[20:21]
	v_pk_add_f32 v[12:13], v[16:17], v[22:23]
	v_pk_add_f32 v[4:5], v[8:9], v[4:5]
	v_pk_add_f32 v[6:7], v[6:7], v[12:13]
	s_nop 0
	v_pk_add_f32 v[4:5], v[4:5], v[6:7]
	s_nop 0
	v_add_f32_e32 v3, v4, v5
	v_fmamk_f32 v3, v3, 0x3a800000, v231
	v_rsq_f32_e32 v3, v3
	ds_write_b32 v2, v3 offset:1024
	s_cmp_lt_u32 2, s100
	s_cbranch_scc0 .Lrta_end
	v_mov_b32_e32 v4, v56
	v_mov_b32_e32 v5, v57
	v_mov_b32_e32 v6, v58
	v_mov_b32_e32 v7, v59
	v_mov_b32_e32 v12, v60
	v_mov_b32_e32 v13, v61
	v_mov_b32_e32 v14, v62
	v_mov_b32_e32 v15, v63
	v_mov_b32_e32 v16, v64
	v_mov_b32_e32 v17, v65
	v_mov_b32_e32 v18, v66
	v_mov_b32_e32 v19, v67
	v_mov_b32_e32 v20, v68
	v_mov_b32_e32 v21, v69
	v_mov_b32_e32 v22, v70
	v_mov_b32_e32 v23, v71
	v_mov_b32_e32 v8, v4
	v_mov_b32_e32 v9, v12
	v_mov_b32_e32 v12, v5
	v_mov_b32_e32 v4, v6
	v_mov_b32_e32 v5, v14
	v_mov_b32_e32 v14, v7
	v_mov_b32_e32 v6, v16
	v_mov_b32_e32 v7, v20
	v_mov_b32_e32 v20, v17
	v_mov_b32_e32 v16, v18
	v_mov_b32_e32 v17, v22
	v_mov_b32_e32 v22, v19
	v_pk_add_f32 v[8:9], v[8:9], v[12:13]
	v_pk_add_f32 v[4:5], v[4:5], v[14:15]
	v_pk_add_f32 v[6:7], v[6:7], v[20:21]
	v_pk_add_f32 v[12:13], v[16:17], v[22:23]
	v_pk_add_f32 v[4:5], v[8:9], v[4:5]
	v_pk_add_f32 v[6:7], v[6:7], v[12:13]
	s_nop 0
	v_pk_add_f32 v[4:5], v[4:5], v[6:7]
	s_nop 0
	v_add_f32_e32 v3, v4, v5
	v_fmamk_f32 v3, v3, 0x3a800000, v231
	v_rsq_f32_e32 v3, v3
	ds_write_b32 v2, v3 offset:2048
	s_cmp_lt_u32 3, s100
	s_cbranch_scc0 .Lrta_end
	v_mov_b32_e32 v4, v72
	v_mov_b32_e32 v5, v73
	v_mov_b32_e32 v6, v74
	v_mov_b32_e32 v7, v75
	v_mov_b32_e32 v12, v76
	v_mov_b32_e32 v13, v77
	v_mov_b32_e32 v14, v78
	v_mov_b32_e32 v15, v79
	v_mov_b32_e32 v16, v80
	v_mov_b32_e32 v17, v81
	v_mov_b32_e32 v18, v82
	v_mov_b32_e32 v19, v83
	v_mov_b32_e32 v20, v84
	v_mov_b32_e32 v21, v85
	v_mov_b32_e32 v22, v86
	v_mov_b32_e32 v23, v87
	v_mov_b32_e32 v8, v4
	v_mov_b32_e32 v9, v12
	v_mov_b32_e32 v12, v5
	v_mov_b32_e32 v4, v6
	v_mov_b32_e32 v5, v14
	v_mov_b32_e32 v14, v7
	v_mov_b32_e32 v6, v16
	v_mov_b32_e32 v7, v20
	v_mov_b32_e32 v20, v17
	v_mov_b32_e32 v16, v18
	v_mov_b32_e32 v17, v22
	v_mov_b32_e32 v22, v19
	v_pk_add_f32 v[8:9], v[8:9], v[12:13]
	v_pk_add_f32 v[4:5], v[4:5], v[14:15]
	v_pk_add_f32 v[6:7], v[6:7], v[20:21]
	v_pk_add_f32 v[12:13], v[16:17], v[22:23]
	v_pk_add_f32 v[4:5], v[8:9], v[4:5]
	v_pk_add_f32 v[6:7], v[6:7], v[12:13]
	s_nop 0
	v_pk_add_f32 v[4:5], v[4:5], v[6:7]
	s_nop 0
	v_add_f32_e32 v3, v4, v5
	v_fmamk_f32 v3, v3, 0x3a800000, v231
	v_rsq_f32_e32 v3, v3
	ds_write_b32 v2, v3 offset:3072
	s_cmp_lt_u32 4, s100
	s_cbranch_scc0 .Lrta_end
	v_mov_b32_e32 v4, v88
	v_mov_b32_e32 v5, v89
	v_mov_b32_e32 v6, v90
	v_mov_b32_e32 v7, v91
	v_mov_b32_e32 v12, v92
	v_mov_b32_e32 v13, v93
	v_mov_b32_e32 v14, v94
	v_mov_b32_e32 v15, v95
	v_mov_b32_e32 v16, v96
	v_mov_b32_e32 v17, v97
	v_mov_b32_e32 v18, v98
	v_mov_b32_e32 v19, v99
	v_mov_b32_e32 v20, v100
	v_mov_b32_e32 v21, v101
	v_mov_b32_e32 v22, v102
	v_mov_b32_e32 v23, v103
	v_mov_b32_e32 v8, v4
	v_mov_b32_e32 v9, v12
	v_mov_b32_e32 v12, v5
	v_mov_b32_e32 v4, v6
	v_mov_b32_e32 v5, v14
	v_mov_b32_e32 v14, v7
	v_mov_b32_e32 v6, v16
	v_mov_b32_e32 v7, v20
	v_mov_b32_e32 v20, v17
	v_mov_b32_e32 v16, v18
	v_mov_b32_e32 v17, v22
	v_mov_b32_e32 v22, v19
	v_pk_add_f32 v[8:9], v[8:9], v[12:13]
	v_pk_add_f32 v[4:5], v[4:5], v[14:15]
	v_pk_add_f32 v[6:7], v[6:7], v[20:21]
	v_pk_add_f32 v[12:13], v[16:17], v[22:23]
	v_pk_add_f32 v[4:5], v[8:9], v[4:5]
	v_pk_add_f32 v[6:7], v[6:7], v[12:13]
	s_nop 0
	v_pk_add_f32 v[4:5], v[4:5], v[6:7]
	s_nop 0
	v_add_f32_e32 v3, v4, v5
	v_fmamk_f32 v3, v3, 0x3a800000, v231
	v_rsq_f32_e32 v3, v3
	ds_write_b32 v2, v3 offset:4096
	s_cmp_lt_u32 5, s100
	s_cbranch_scc0 .Lrta_end
	v_mov_b32_e32 v4, v104
	v_mov_b32_e32 v5, v105
	v_mov_b32_e32 v6, v106
	v_mov_b32_e32 v7, v107
	v_mov_b32_e32 v12, v108
	v_mov_b32_e32 v13, v109
	v_mov_b32_e32 v14, v110
	v_mov_b32_e32 v15, v111
	v_mov_b32_e32 v16, v112
	v_mov_b32_e32 v17, v113
	v_mov_b32_e32 v18, v114
	v_mov_b32_e32 v19, v115
	v_mov_b32_e32 v20, v116
	v_mov_b32_e32 v21, v117
	v_mov_b32_e32 v22, v118
	v_mov_b32_e32 v23, v119
	v_mov_b32_e32 v8, v4
	v_mov_b32_e32 v9, v12
	v_mov_b32_e32 v12, v5
	v_mov_b32_e32 v4, v6
	v_mov_b32_e32 v5, v14
	v_mov_b32_e32 v14, v7
	v_mov_b32_e32 v6, v16
	v_mov_b32_e32 v7, v20
	v_mov_b32_e32 v20, v17
	v_mov_b32_e32 v16, v18
	v_mov_b32_e32 v17, v22
	v_mov_b32_e32 v22, v19
	v_pk_add_f32 v[8:9], v[8:9], v[12:13]
	v_pk_add_f32 v[4:5], v[4:5], v[14:15]
	v_pk_add_f32 v[6:7], v[6:7], v[20:21]
	v_pk_add_f32 v[12:13], v[16:17], v[22:23]
	v_pk_add_f32 v[4:5], v[8:9], v[4:5]
	v_pk_add_f32 v[6:7], v[6:7], v[12:13]
	s_nop 0
	v_pk_add_f32 v[4:5], v[4:5], v[6:7]
	s_nop 0
	v_add_f32_e32 v3, v4, v5
	v_fmamk_f32 v3, v3, 0x3a800000, v231
	v_rsq_f32_e32 v3, v3
	ds_write_b32 v2, v3 offset:5120
.Lrta_end:
	s_mov_b64 exec, vcc
	s_add_i32 s0, s31, s34
	s_mul_hi_i32 s1, s0, 0x2e8ba2e9
	s_lshr_b32 s16, s1, 31
	s_ashr_i32 s1, s1, 5
	s_add_i32 s1, s1, s16
	s_lshl_b32 s16, s1, 3
	s_sub_i32 s17, 0x41, s16
	s_min_u32 s17, s17, 8
	s_mulk_i32 s1, 0xb0
	s_sub_i32 s18, s0, s1
	v_cvt_f32_ubyte0_e32 v2, s17
	v_cvt_f32_i32_e32 v0, s18
	v_rcp_iflag_f32_e32 v3, v2
	s_ashr_i32 s0, s18, 30
	s_or_b32 s19, s0, 1
	s_waitcnt lgkmcnt(0)
	v_mul_f32_e32 v3, v0, v3
	v_trunc_f32_e32 v3, v3
	v_fma_f32 v0, -v3, v2, v0
	v_cmp_ge_f32_e64 s[0:1], |v0|, v2
	v_ashrrev_i32_e32 v0, 31, v10
	v_lshrrev_b32_e32 v0, 26, v0
	v_add_u32_e32 v0, v10, v0
	v_ashrrev_i32_e32 v11, 6, v0
	v_bfe_i32 v0, v10, 27, 1
	v_cvt_i32_f32_e32 v3, v3
	v_lshlrev_b32_e32 v2, 4, v10
	v_lshrrev_b32_e32 v0, 22, v0
	v_add_u32_e32 v0, v2, v0
	v_and_b32_e32 v0, 0xfffffc00, v0
	s_and_b64 s[0:1], s[0:1], exec
	v_sub_u32_e32 v0, v2, v0
	v_readfirstlane_b32 s1, v3
	v_lshrrev_b32_e32 v3, 4, v0
	v_bitop3_b32 v0, v3, v0, 32 bitop3:0x6c
	v_ashrrev_i32_e32 v4, 31, v0
	s_cselect_b32 s0, s19, 0
	v_lshrrev_b32_e32 v4, 26, v4
	s_add_i32 s0, s1, s0
	v_add_u32_e32 v4, v0, v4
	s_mul_i32 s1, s0, s17
	v_lshlrev_b32_e32 v3, 3, v11
	v_ashrrev_i32_e32 v12, 6, v4
	v_and_b32_e32 v4, 0xc0, v4
	s_sub_i32 s1, s18, s1
	v_and_b32_e32 v3, -16, v3
	v_sub_u32_e32 v0, v0, v4
	s_sext_i32_i16 s1, s1
	v_add_u32_e32 v3, v12, v3
	v_ashrrev_i16_sdwa v0, v232, sext(v0) dst_sel:DWORD dst_unused:UNUSED_PAD src0_sel:DWORD src1_sel:BYTE_0
	s_add_i32 s38, s16, s1
	s_bfe_i64 s[40:41], s[0:1], 0x100000
	v_lshlrev_b32_e32 v5, 5, v11
	v_bfe_i32 v13, v0, 0, 16
	v_lshlrev_b32_e32 v0, 1, v3
	v_lshrrev_b32_e32 v4, 2, v3
	v_and_b32_e32 v6, 3, v12
	s_mov_b32 s1, 0x1fffe0
	v_and_b32_e32 v5, 32, v5
	v_and_b32_e32 v0, 24, v0
	v_and_b32_e32 v4, 4, v4
	v_and_or_b32 v6, v3, s1, v6
	v_or3_b32 v0, v6, v4, v0
	v_add_lshl_u32 v4, v5, v13, 1
	v_add_u32_e32 v2, 0x2000, v2
	v_lshl_add_u32 v130, v3, 11, v4
	v_ashrrev_i32_e32 v3, 31, v2
	v_lshrrev_b32_e32 v3, 22, v3
	v_add_u32_e32 v3, v2, v3
	v_ashrrev_i32_e32 v14, 10, v3
	v_mul_i32_i24_e32 v3, 0x400, v14
	v_sub_u32_e32 v2, v2, v3
	v_lshrrev_b32_e32 v3, 4, v2
	v_bitop3_b32 v2, v3, v2, 32 bitop3:0x6c
	v_lshl_add_u32 v0, v0, 11, v4
	v_ashrrev_i32_e32 v4, 31, v2
	v_lshrrev_b32_e32 v4, 26, v4
	v_lshlrev_b32_e32 v3, 3, v14
	v_add_u32_e32 v4, v2, v4
	v_and_b32_e32 v3, -16, v3
	v_ashrrev_i32_e32 v15, 6, v4
	v_add_u32_e32 v3, v15, v3
	v_and_b32_e32 v6, 3, v15
	v_and_or_b32 v6, v3, s1, v6
	s_ashr_i32 s1, s30, 6
	s_ashr_i32 s39, s38, 31
	s_ashr_i32 s0, s30, 8
	s_lshl_b32 s28, s1, 10
	s_add_u32 s48, s6, 0xb900000
	v_readlane_b32 s16, v253, 36
	s_addc_u32 s49, s7, 0
	s_mul_i32 s16, s16, 0x3980000
	v_readlane_b32 s17, v253, 37
	s_add_u32 s16, s6, s16
	s_addc_u32 s17, s7, 0
	v_and_b32_e32 v4, 0xc0, v4
	s_add_u32 s50, s16, 0x100000
	v_sub_u32_e32 v2, v2, v4
	s_addc_u32 s51, s17, 0
	s_lshl_b64 s[16:17], s[38:39], 19
	s_lshl_b64 s[18:19], s[40:41], 19
	v_ashrrev_i16_sdwa v2, v232, sext(v2) dst_sel:DWORD dst_unused:UNUSED_PAD src0_sel:DWORD src1_sel:BYTE_0
	s_add_u32 s44, s50, s18
	v_lshlrev_b32_e32 v5, 5, v14
	v_bfe_i32 v16, v2, 0, 16
	v_lshlrev_b32_e32 v2, 1, v3
	v_lshrrev_b32_e32 v4, 2, v3
	s_addc_u32 s45, s51, s19
	s_add_i32 s41, s28, 0
	v_and_b32_e32 v5, 32, v5
	v_and_b32_e32 v2, 24, v2
	v_and_b32_e32 v4, 4, v4
	s_add_i32 m0, s41, 0x10000
	v_or3_b32 v2, v6, v4, v2
	v_add_lshl_u32 v4, v5, v16, 1
	s_barrier
	global_load_lds_dwordx4 v0, s[44:45]
	s_add_i32 m0, s41, 0x12000
	v_lshl_add_u32 v134, v2, 11, v4
	s_add_u32 s18, s44, 0x40000
	global_load_lds_dwordx4 v134, s[44:45]
	s_addc_u32 s19, s45, 0
	s_add_i32 m0, s41, 0x14000
	v_lshl_add_u32 v132, v3, 11, v4
	global_load_lds_dwordx4 v0, s[18:19]
	s_add_i32 m0, s41, 0x16000
	s_add_u32 s42, s48, s16
	s_addc_u32 s43, s49, s17
	s_add_i32 s52, s41, 0x2000
	global_load_lds_dwordx4 v134, s[18:19]
	s_mov_b32 m0, s41
	s_add_u32 s16, s42, 0x40000
	global_load_lds_dwordx4 v130, s[42:43]
	s_mov_b32 m0, s52
	s_addc_u32 s17, s43, 0
	s_add_i32 s53, s41, 0x4000
	global_load_lds_dwordx4 v132, s[42:43]
	s_mov_b32 m0, s53
	s_add_i32 s54, s41, 0x6000
	global_load_lds_dwordx4 v130, s[16:17]
	s_mov_b32 m0, s54
	s_cmp_eq_u32 s0, 1
	global_load_lds_dwordx4 v132, s[16:17]
	v_mov_b32_e32 v135, v1
	v_mov_b32_e32 v131, v1
	v_mov_b32_e32 v133, v1
	s_cselect_b64 s[16:17], -1, 0
	v_lshl_add_u64 v[8:9], s[44:45], 0, v[0:1]
	v_lshl_add_u64 v[6:7], s[44:45], 0, v[134:135]
	v_lshl_add_u64 v[4:5], s[42:43], 0, v[130:131]
	v_lshl_add_u64 v[2:3], s[42:43], 0, v[132:133]
	s_and_b64 vcc, exec, s[16:17]
	s_cbranch_vccz .LBB0_704
	s_barrier

.LBB0_1062:
	s_andn2_b64 vcc, exec, s[0:1]
	s_cbranch_vccnz .LBB0_1140
	v_readlane_b32 s0, v253, 36
	v_readlane_b32 s1, v253, 37
	s_mul_i32 s28, s0, 0xc3000
	s_lshl_b64 s[0:1], s[28:29], 2
	s_add_u32 s0, s8, s0
	s_addc_u32 s1, s9, s1
	s_add_u32 s2, s0, 0x4395e400
	s_movk_i32 s0, 0x100
	v_readlane_b32 s5, v254, 24
	s_addc_u32 s3, s1, 0
	s_ashr_i32 s25, s24, 31
	v_cmp_gt_i32_e64 s[0:1], s0, v10
	v_lshl_add_u32 v2, v10, 2, s5
	s_mov_b64 s[18:19], s[16:17]
	s_mov_b32 s100, 0
	s_branch .LBB0_1066

.LBB0_1072:
	s_ashr_i32 s5, s5, 3
	s_add_i32 s5, s28, s5
	s_mul_hi_i32 s28, s5, 0xea0ea0eb
	s_add_i32 s28, s28, s5
	s_lshr_b32 s31, s28, 31
	s_ashr_i32 s28, s28, 8
	s_add_i32 s28, s28, s31
	s_lshl_b32 s31, s28, 3
	s_sub_i32 s34, 0x41, s31
	s_min_i32 s34, s34, 8
	s_abs_i32 s34, s34
	v_cvt_f32_u32_e32 v3, s34
	s_sub_i32 s35, 0, s34
	s_mulk_i32 s28, 0x118
	s_sub_i32 s5, s5, s28
	v_rcp_iflag_f32_e32 v3, v3
	s_ashr_i32 s28, s5, 31
	s_abs_i32 s5, s5
	v_mul_f32_e32 v3, 0x4f7ffffe, v3
	v_cvt_u32_f32_e32 v3, v3
	s_nop 0
	v_readfirstlane_b32 s36, v3
	s_mul_i32 s35, s35, s36
	s_mul_hi_u32 s35, s36, s35
	s_add_i32 s36, s36, s35
	s_mul_hi_u32 s35, s5, s36
	s_mul_i32 s35, s35, s34
	s_sub_i32 s5, s5, s35
	s_sub_i32 s35, s5, s34
	s_cmp_ge_u32 s5, s34
	s_cselect_b32 s5, s35, s5
	s_sub_i32 s35, s5, s34
	s_cmp_ge_u32 s5, s34
	s_cselect_b32 s5, s35, s5
	s_xor_b32 s5, s5, s28
	s_sub_i32 s5, s5, s28
	s_add_i32 s5, s5, s31
	s_mov_b32 m0, s100
	s_nop 0
	v_writelane_b32 v255, s5, m0
	s_branch .LBB0_1064
.LBB0_1073:
	s_and_saveexec_b64 vcc, s[0:1]
	s_cbranch_execz .Lrtb_end
	s_cmp_lt_u32 0, s100
	s_cbranch_scc0 .Lrtb_wait
	v_readlane_b32 s101, v255, 0
	s_nop 0
	v_lshl_add_u32 v4, s101, 8, v10
	v_ashrrev_i32_e32 v5, 31, v4
	v_lshlrev_b64 v[4:5], 6, v[4:5]
	v_lshl_add_u64 v[8:9], s[2:3], 0, v[4:5]
	global_load_dwordx4 v[24:27], v[8:9], off
	global_load_dwordx4 v[28:31], v[8:9], off offset:32
	global_load_dwordx4 v[32:35], v[8:9], off offset:16
	global_load_dwordx4 v[36:39], v[8:9], off offset:48
	s_cmp_lt_u32 1, s100
	s_cbranch_scc0 .Lrtb_wait
	v_readlane_b32 s101, v255, 1
	s_nop 0
	v_lshl_add_u32 v4, s101, 8, v10
	v_ashrrev_i32_e32 v5, 31, v4
	v_lshlrev_b64 v[4:5], 6, v[4:5]
	v_lshl_add_u64 v[8:9], s[2:3], 0, v[4:5]
	global_load_dwordx4 v[40:43], v[8:9], off
	global_load_dwordx4 v[44:47], v[8:9], off offset:32
	global_load_dwordx4 v[48:51], v[8:9], off offset:16
	global_load_dwordx4 v[52:55], v[8:9], off offset:48
	s_cmp_lt_u32 2, s100
	s_cbranch_scc0 .Lrtb_wait
	v_readlane_b32 s101, v255, 2
	s_nop 0
	v_lshl_add_u32 v4, s101, 8, v10
	v_ashrrev_i32_e32 v5, 31, v4
	v_lshlrev_b64 v[4:5], 6, v[4:5]
	v_lshl_add_u64 v[8:9], s[2:3], 0, v[4:5]
	global_load_dwordx4 v[56:59], v[8:9], off
	global_load_dwordx4 v[60:63], v[8:9], off offset:32
	global_load_dwordx4 v[64:67], v[8:9], off offset:16
	global_load_dwordx4 v[68:71], v[8:9], off offset:48
	s_cmp_lt_u32 3, s100
	s_cbranch_scc0 .Lrtb_wait
	v_readlane_b32 s101, v255, 3
	s_nop 0
	v_lshl_add_u32 v4, s101, 8, v10
	v_ashrrev_i32_e32 v5, 31, v4
	v_lshlrev_b64 v[4:5], 6, v[4:5]
	v_lshl_add_u64 v[8:9], s[2:3], 0, v[4:5]
	global_load_dwordx4 v[72:75], v[8:9], off
	global_load_dwordx4 v[76:79], v[8:9], off offset:32
	global_load_dwordx4 v[80:83], v[8:9], off offset:16
	global_load_dwordx4 v[84:87], v[8:9], off offset:48
	s_cmp_lt_u32 4, s100
	s_cbranch_scc0 .Lrtb_wait
	v_readlane_b32 s101, v255, 4
	s_nop 0
	v_lshl_add_u32 v4, s101, 8, v10
	v_ashrrev_i32_e32 v5, 31, v4
	v_lshlrev_b64 v[4:5], 6, v[4:5]
	v_lshl_add_u64 v[8:9], s[2:3], 0, v[4:5]
	global_load_dwordx4 v[88:91], v[8:9], off
	global_load_dwordx4 v[92:95], v[8:9], off offset:32
	global_load_dwordx4 v[96:99], v[8:9], off offset:16
	global_load_dwordx4 v[100:103], v[8:9], off offset:48
	s_cmp_lt_u32 5, s100
	s_cbranch_scc0 .Lrtb_wait
	v_readlane_b32 s101, v255, 5
	s_nop 0
	v_lshl_add_u32 v4, s101, 8, v10
	v_ashrrev_i32_e32 v5, 31, v4
	v_lshlrev_b64 v[4:5], 6, v[4:5]
	v_lshl_add_u64 v[8:9], s[2:3], 0, v[4:5]
	global_load_dwordx4 v[104:107], v[8:9], off
	global_load_dwordx4 v[108:111], v[8:9], off offset:32
	global_load_dwordx4 v[112:115], v[8:9], off offset:16
	global_load_dwordx4 v[116:119], v[8:9], off offset:48
	s_cmp_lt_u32 6, s100
	s_cbranch_scc0 .Lrtb_wait
	v_readlane_b32 s101, v255, 6
	s_nop 0
	v_lshl_add_u32 v4, s101, 8, v10
	v_ashrrev_i32_e32 v5, 31, v4
	v_lshlrev_b64 v[4:5], 6, v[4:5]
	v_lshl_add_u64 v[8:9], s[2:3], 0, v[4:5]
	global_load_dwordx4 v[120:123], v[8:9], off
	global_load_dwordx4 v[124:127], v[8:9], off offset:32
	global_load_dwordx4 v[128:131], v[8:9], off offset:16
	global_load_dwordx4 v[132:135], v[8:9], off offset:48
	s_cmp_lt_u32 7, s100
	s_cbranch_scc0 .Lrtb_wait
	v_readlane_b32 s101, v255, 7
	s_nop 0
	v_lshl_add_u32 v4, s101, 8, v10
	v_ashrrev_i32_e32 v5, 31, v4
	v_lshlrev_b64 v[4:5], 6, v[4:5]
	v_lshl_add_u64 v[8:9], s[2:3], 0, v[4:5]
	global_load_dwordx4 v[136:139], v[8:9], off
	global_load_dwordx4 v[140:143], v[8:9], off offset:32
	global_load_dwordx4 v[144:147], v[8:9], off offset:16
	global_load_dwordx4 v[148:151], v[8:9], off offset:48
	s_cmp_lt_u32 8, s100
	s_cbranch_scc0 .Lrtb_wait
	v_readlane_b32 s101, v255, 8
	s_nop 0
	v_lshl_add_u32 v4, s101, 8, v10
	v_ashrrev_i32_e32 v5, 31, v4
	v_lshlrev_b64 v[4:5], 6, v[4:5]
	v_lshl_add_u64 v[8:9], s[2:3], 0, v[4:5]
	global_load_dwordx4 v[152:155], v[8:9], off
	global_load_dwordx4 v[156:159], v[8:9], off offset:32
	global_load_dwordx4 v[160:163], v[8:9], off offset:16
	global_load_dwordx4 v[164:167], v[8:9], off offset:48
.Lrtb_wait:
	s_waitcnt vmcnt(0)
	s_cmp_lt_u32 0, s100
	s_cbranch_scc0 .Lrtb_end
	v_mov_b32_e32 v4, v24
	v_mov_b32_e32 v5, v25
	v_mov_b32_e32 v6, v26
	v_mov_b32_e32 v7, v27
	v_mov_b32_e32 v12, v28
	v_mov_b32_e32 v13, v29
	v_mov_b32_e32 v14, v30
	v_mov_b32_e32 v15, v31
	v_mov_b32_e32 v16, v32
	v_mov_b32_e32 v17, v33
	v_mov_b32_e32 v18, v34
	v_mov_b32_e32 v19, v35
	v_mov_b32_e32 v20, v36
	v_mov_b32_e32 v21, v37
	v_mov_b32_e32 v22, v38
	v_mov_b32_e32 v23, v39
	v_mov_b32_e32 v8, v4
	v_mov_b32_e32 v9, v12
	v_mov_b32_e32 v12, v5
	v_mov_b32_e32 v4, v6
	v_mov_b32_e32 v5, v14
	v_mov_b32_e32 v14, v7
	v_mov_b32_e32 v6, v16
	v_mov_b32_e32 v7, v20
	v_mov_b32_e32 v20, v17
	v_mov_b32_e32 v16, v18
	v_mov_b32_e32 v17, v22
	v_mov_b32_e32 v22, v19
	v_pk_add_f32 v[8:9], v[8:9], v[12:13]
	v_pk_add_f32 v[4:5], v[4:5], v[14:15]
	v_pk_add_f32 v[6:7], v[6:7], v[20:21]
	v_pk_add_f32 v[12:13], v[16:17], v[22:23]
	v_pk_add_f32 v[4:5], v[8:9], v[4:5]
	v_pk_add_f32 v[6:7], v[6:7], v[12:13]
	s_nop 0
	v_pk_add_f32 v[4:5], v[4:5], v[6:7]
	s_nop 0
	v_add_f32_e32 v3, v4, v5
	v_fmamk_f32 v3, v3, 0x3a800000, v231
	v_rsq_f32_e32 v3, v3
	ds_write_b32 v2, v3
	s_cmp_lt_u32 1, s100
	s_cbranch_scc0 .Lrtb_end
	v_mov_b32_e32 v4, v40
	v_mov_b32_e32 v5, v41
	v_mov_b32_e32 v6, v42
	v_mov_b32_e32 v7, v43
	v_mov_b32_e32 v12, v44
	v_mov_b32_e32 v13, v45
	v_mov_b32_e32 v14, v46
	v_mov_b32_e32 v15, v47
	v_mov_b32_e32 v16, v48
	v_mov_b32_e32 v17, v49
	v_mov_b32_e32 v18, v50
	v_mov_b32_e32 v19, v51
	v_mov_b32_e32 v20, v52
	v_mov_b32_e32 v21, v53
	v_mov_b32_e32 v22, v54
	v_mov_b32_e32 v23, v55
	v_mov_b32_e32 v8, v4
	v_mov_b32_e32 v9, v12
	v_mov_b32_e32 v12, v5
	v_mov_b32_e32 v4, v6
	v_mov_b32_e32 v5, v14
	v_mov_b32_e32 v14, v7
	v_mov_b32_e32 v6, v16
	v_mov_b32_e32 v7, v20
	v_mov_b32_e32 v20, v17
	v_mov_b32_e32 v16, v18
	v_mov_b32_e32 v17, v22
	v_mov_b32_e32 v22, v19
	v_pk_add_f32 v[8:9], v[8:9], v[12:13]
	v_pk_add_f32 v[4:5], v[4:5], v[14:15]
	v_pk_add_f32 v[6:7], v[6:7], v[20:21]
	v_pk_add_f32 v[12:13], v[16:17], v[22:23]
	v_pk_add_f32 v[4:5], v[8:9], v[4:5]
	v_pk_add_f32 v[6:7], v[6:7], v[12:13]
	s_nop 0
	v_pk_add_f32 v[4:5], v[4:5], v[6:7]
	s_nop 0
	v_add_f32_e32 v3, v4, v5
	v_fmamk_f32 v3, v3, 0x3a800000, v231
	v_rsq_f32_e32 v3, v3
	ds_write_b32 v2, v3 offset:1024
	s_cmp_lt_u32 2, s100
	s_cbranch_scc0 .Lrtb_end
	v_mov_b32_e32 v4, v56
	v_mov_b32_e32 v5, v57
	v_mov_b32_e32 v6, v58
	v_mov_b32_e32 v7, v59
	v_mov_b32_e32 v12, v60
	v_mov_b32_e32 v13, v61
	v_mov_b32_e32 v14, v62
	v_mov_b32_e32 v15, v63
	v_mov_b32_e32 v16, v64
	v_mov_b32_e32 v17, v65
	v_mov_b32_e32 v18, v66
	v_mov_b32_e32 v19, v67
	v_mov_b32_e32 v20, v68
	v_mov_b32_e32 v21, v69
	v_mov_b32_e32 v22, v70
	v_mov_b32_e32 v23, v71
	v_mov_b32_e32 v8, v4
	v_mov_b32_e32 v9, v12
	v_mov_b32_e32 v12, v5
	v_mov_b32_e32 v4, v6
	v_mov_b32_e32 v5, v14
	v_mov_b32_e32 v14, v7
	v_mov_b32_e32 v6, v16
	v_mov_b32_e32 v7, v20
	v_mov_b32_e32 v20, v17
	v_mov_b32_e32 v16, v18
	v_mov_b32_e32 v17, v22
	v_mov_b32_e32 v22, v19
	v_pk_add_f32 v[8:9], v[8:9], v[12:13]
	v_pk_add_f32 v[4:5], v[4:5], v[14:15]
	v_pk_add_f32 v[6:7], v[6:7], v[20:21]
	v_pk_add_f32 v[12:13], v[16:17], v[22:23]
	v_pk_add_f32 v[4:5], v[8:9], v[4:5]
	v_pk_add_f32 v[6:7], v[6:7], v[12:13]
	s_nop 0
	v_pk_add_f32 v[4:5], v[4:5], v[6:7]
	s_nop 0
	v_add_f32_e32 v3, v4, v5
	v_fmamk_f32 v3, v3, 0x3a800000, v231
	v_rsq_f32_e32 v3, v3
	ds_write_b32 v2, v3 offset:2048
	s_cmp_lt_u32 3, s100
	s_cbranch_scc0 .Lrtb_end
	v_mov_b32_e32 v4, v72
	v_mov_b32_e32 v5, v73
	v_mov_b32_e32 v6, v74
	v_mov_b32_e32 v7, v75
	v_mov_b32_e32 v12, v76
	v_mov_b32_e32 v13, v77
	v_mov_b32_e32 v14, v78
	v_mov_b32_e32 v15, v79
	v_mov_b32_e32 v16, v80
	v_mov_b32_e32 v17, v81
	v_mov_b32_e32 v18, v82
	v_mov_b32_e32 v19, v83
	v_mov_b32_e32 v20, v84
	v_mov_b32_e32 v21, v85
	v_mov_b32_e32 v22, v86
	v_mov_b32_e32 v23, v87
	v_mov_b32_e32 v8, v4
	v_mov_b32_e32 v9, v12
	v_mov_b32_e32 v12, v5
	v_mov_b32_e32 v4, v6
	v_mov_b32_e32 v5, v14
	v_mov_b32_e32 v14, v7
	v_mov_b32_e32 v6, v16
	v_mov_b32_e32 v7, v20
	v_mov_b32_e32 v20, v17
	v_mov_b32_e32 v16, v18
	v_mov_b32_e32 v17, v22
	v_mov_b32_e32 v22, v19
	v_pk_add_f32 v[8:9], v[8:9], v[12:13]
	v_pk_add_f32 v[4:5], v[4:5], v[14:15]
	v_pk_add_f32 v[6:7], v[6:7], v[20:21]
	v_pk_add_f32 v[12:13], v[16:17], v[22:23]
	v_pk_add_f32 v[4:5], v[8:9], v[4:5]
	v_pk_add_f32 v[6:7], v[6:7], v[12:13]
	s_nop 0
	v_pk_add_f32 v[4:5], v[4:5], v[6:7]
	s_nop 0
	v_add_f32_e32 v3, v4, v5
	v_fmamk_f32 v3, v3, 0x3a800000, v231
	v_rsq_f32_e32 v3, v3
	ds_write_b32 v2, v3 offset:3072
	s_cmp_lt_u32 4, s100
	s_cbranch_scc0 .Lrtb_end
	v_mov_b32_e32 v4, v88
	v_mov_b32_e32 v5, v89
	v_mov_b32_e32 v6, v90
	v_mov_b32_e32 v7, v91
	v_mov_b32_e32 v12, v92
	v_mov_b32_e32 v13, v93
	v_mov_b32_e32 v14, v94
	v_mov_b32_e32 v15, v95
	v_mov_b32_e32 v16, v96
	v_mov_b32_e32 v17, v97
	v_mov_b32_e32 v18, v98
	v_mov_b32_e32 v19, v99
	v_mov_b32_e32 v20, v100
	v_mov_b32_e32 v21, v101
	v_mov_b32_e32 v22, v102
	v_mov_b32_e32 v23, v103
	v_mov_b32_e32 v8, v4
	v_mov_b32_e32 v9, v12
	v_mov_b32_e32 v12, v5
	v_mov_b32_e32 v4, v6
	v_mov_b32_e32 v5, v14
	v_mov_b32_e32 v14, v7
	v_mov_b32_e32 v6, v16
	v_mov_b32_e32 v7, v20
	v_mov_b32_e32 v20, v17
	v_mov_b32_e32 v16, v18
	v_mov_b32_e32 v17, v22
	v_mov_b32_e32 v22, v19
	v_pk_add_f32 v[8:9], v[8:9], v[12:13]
	v_pk_add_f32 v[4:5], v[4:5], v[14:15]
	v_pk_add_f32 v[6:7], v[6:7], v[20:21]
	v_pk_add_f32 v[12:13], v[16:17], v[22:23]
	v_pk_add_f32 v[4:5], v[8:9], v[4:5]
	v_pk_add_f32 v[6:7], v[6:7], v[12:13]
	s_nop 0
	v_pk_add_f32 v[4:5], v[4:5], v[6:7]
	s_nop 0
	v_add_f32_e32 v3, v4, v5
	v_fmamk_f32 v3, v3, 0x3a800000, v231
	v_rsq_f32_e32 v3, v3
	ds_write_b32 v2, v3 offset:4096
	s_cmp_lt_u32 5, s100
	s_cbranch_scc0 .Lrtb_end
	v_mov_b32_e32 v4, v104
	v_mov_b32_e32 v5, v105
	v_mov_b32_e32 v6, v106
	v_mov_b32_e32 v7, v107
	v_mov_b32_e32 v12, v108
	v_mov_b32_e32 v13, v109
	v_mov_b32_e32 v14, v110
	v_mov_b32_e32 v15, v111
	v_mov_b32_e32 v16, v112
	v_mov_b32_e32 v17, v113
	v_mov_b32_e32 v18, v114
	v_mov_b32_e32 v19, v115
	v_mov_b32_e32 v20, v116
	v_mov_b32_e32 v21, v117
	v_mov_b32_e32 v22, v118
	v_mov_b32_e32 v23, v119
	v_mov_b32_e32 v8, v4
	v_mov_b32_e32 v9, v12
	v_mov_b32_e32 v12, v5
	v_mov_b32_e32 v4, v6
	v_mov_b32_e32 v5, v14
	v_mov_b32_e32 v14, v7
	v_mov_b32_e32 v6, v16
	v_mov_b32_e32 v7, v20
	v_mov_b32_e32 v20, v17
	v_mov_b32_e32 v16, v18
	v_mov_b32_e32 v17, v22
	v_mov_b32_e32 v22, v19
	v_pk_add_f32 v[8:9], v[8:9], v[12:13]
	v_pk_add_f32 v[4:5], v[4:5], v[14:15]
	v_pk_add_f32 v[6:7], v[6:7], v[20:21]
	v_pk_add_f32 v[12:13], v[16:17], v[22:23]
	v_pk_add_f32 v[4:5], v[8:9], v[4:5]
	v_pk_add_f32 v[6:7], v[6:7], v[12:13]
	s_nop 0
	v_pk_add_f32 v[4:5], v[4:5], v[6:7]
	s_nop 0
	v_add_f32_e32 v3, v4, v5
	v_fmamk_f32 v3, v3, 0x3a800000, v231
	v_rsq_f32_e32 v3, v3
	ds_write_b32 v2, v3 offset:5120
	s_cmp_lt_u32 6, s100
	s_cbranch_scc0 .Lrtb_end
	v_mov_b32_e32 v4, v120
	v_mov_b32_e32 v5, v121
	v_mov_b32_e32 v6, v122
	v_mov_b32_e32 v7, v123
	v_mov_b32_e32 v12, v124
	v_mov_b32_e32 v13, v125
	v_mov_b32_e32 v14, v126
	v_mov_b32_e32 v15, v127
	v_mov_b32_e32 v16, v128
	v_mov_b32_e32 v17, v129
	v_mov_b32_e32 v18, v130
	v_mov_b32_e32 v19, v131
	v_mov_b32_e32 v20, v132
	v_mov_b32_e32 v21, v133
	v_mov_b32_e32 v22, v134
	v_mov_b32_e32 v23, v135
	v_mov_b32_e32 v8, v4
	v_mov_b32_e32 v9, v12
	v_mov_b32_e32 v12, v5
	v_mov_b32_e32 v4, v6
	v_mov_b32_e32 v5, v14
	v_mov_b32_e32 v14, v7
	v_mov_b32_e32 v6, v16
	v_mov_b32_e32 v7, v20
	v_mov_b32_e32 v20, v17
	v_mov_b32_e32 v16, v18
	v_mov_b32_e32 v17, v22
	v_mov_b32_e32 v22, v19
	v_pk_add_f32 v[8:9], v[8:9], v[12:13]
	v_pk_add_f32 v[4:5], v[4:5], v[14:15]
	v_pk_add_f32 v[6:7], v[6:7], v[20:21]
	v_pk_add_f32 v[12:13], v[16:17], v[22:23]
	v_pk_add_f32 v[4:5], v[8:9], v[4:5]
	v_pk_add_f32 v[6:7], v[6:7], v[12:13]
	s_nop 0
	v_pk_add_f32 v[4:5], v[4:5], v[6:7]
	s_nop 0
	v_add_f32_e32 v3, v4, v5
	v_fmamk_f32 v3, v3, 0x3a800000, v231
	v_rsq_f32_e32 v3, v3
	ds_write_b32 v2, v3 offset:6144
	s_cmp_lt_u32 7, s100
	s_cbranch_scc0 .Lrtb_end
	v_mov_b32_e32 v4, v136
	v_mov_b32_e32 v5, v137
	v_mov_b32_e32 v6, v138
	v_mov_b32_e32 v7, v139
	v_mov_b32_e32 v12, v140
	v_mov_b32_e32 v13, v141
	v_mov_b32_e32 v14, v142
	v_mov_b32_e32 v15, v143
	v_mov_b32_e32 v16, v144
	v_mov_b32_e32 v17, v145
	v_mov_b32_e32 v18, v146
	v_mov_b32_e32 v19, v147
	v_mov_b32_e32 v20, v148
	v_mov_b32_e32 v21, v149
	v_mov_b32_e32 v22, v150
	v_mov_b32_e32 v23, v151
	v_mov_b32_e32 v8, v4
	v_mov_b32_e32 v9, v12
	v_mov_b32_e32 v12, v5
	v_mov_b32_e32 v4, v6
	v_mov_b32_e32 v5, v14
	v_mov_b32_e32 v14, v7
	v_mov_b32_e32 v6, v16
	v_mov_b32_e32 v7, v20
	v_mov_b32_e32 v20, v17
	v_mov_b32_e32 v16, v18
	v_mov_b32_e32 v17, v22
	v_mov_b32_e32 v22, v19
	v_pk_add_f32 v[8:9], v[8:9], v[12:13]
	v_pk_add_f32 v[4:5], v[4:5], v[14:15]
	v_pk_add_f32 v[6:7], v[6:7], v[20:21]
	v_pk_add_f32 v[12:13], v[16:17], v[22:23]
	v_pk_add_f32 v[4:5], v[8:9], v[4:5]
	v_pk_add_f32 v[6:7], v[6:7], v[12:13]
	s_nop 0
	v_pk_add_f32 v[4:5], v[4:5], v[6:7]
	s_nop 0
	v_add_f32_e32 v3, v4, v5
	v_fmamk_f32 v3, v3, 0x3a800000, v231
	v_rsq_f32_e32 v3, v3
	ds_write_b32 v2, v3 offset:7168
	s_cmp_lt_u32 8, s100
	s_cbranch_scc0 .Lrtb_end
	v_mov_b32_e32 v4, v152
	v_mov_b32_e32 v5, v153
	v_mov_b32_e32 v6, v154
	v_mov_b32_e32 v7, v155
	v_mov_b32_e32 v12, v156
	v_mov_b32_e32 v13, v157
	v_mov_b32_e32 v14, v158
	v_mov_b32_e32 v15, v159
	v_mov_b32_e32 v16, v160
	v_mov_b32_e32 v17, v161
	v_mov_b32_e32 v18, v162
	v_mov_b32_e32 v19, v163
	v_mov_b32_e32 v20, v164
	v_mov_b32_e32 v21, v165
	v_mov_b32_e32 v22, v166
	v_mov_b32_e32 v23, v167
	v_mov_b32_e32 v8, v4
	v_mov_b32_e32 v9, v12
	v_mov_b32_e32 v12, v5
	v_mov_b32_e32 v4, v6
	v_mov_b32_e32 v5, v14
	v_mov_b32_e32 v14, v7
	v_mov_b32_e32 v6, v16
	v_mov_b32_e32 v7, v20
	v_mov_b32_e32 v20, v17
	v_mov_b32_e32 v16, v18
	v_mov_b32_e32 v17, v22
	v_mov_b32_e32 v22, v19
	v_pk_add_f32 v[8:9], v[8:9], v[12:13]
	v_pk_add_f32 v[4:5], v[4:5], v[14:15]
	v_pk_add_f32 v[6:7], v[6:7], v[20:21]
	v_pk_add_f32 v[12:13], v[16:17], v[22:23]
	v_pk_add_f32 v[4:5], v[8:9], v[4:5]
	v_pk_add_f32 v[6:7], v[6:7], v[12:13]
	s_nop 0
	v_pk_add_f32 v[4:5], v[4:5], v[6:7]
	s_nop 0
	v_add_f32_e32 v3, v4, v5
	v_fmamk_f32 v3, v3, 0x3a800000, v231
	v_rsq_f32_e32 v3, v3
	ds_write_b32 v2, v3 offset:8192
.Lrtb_end:
	s_mov_b64 exec, vcc
	v_ashrrev_i32_e32 v3, 31, v0
	v_lshrrev_b32_e32 v3, 26, v3
	v_add_u32_e32 v3, v0, v3
	v_ashrrev_i32_e32 v10, 6, v3
	v_bfe_i32 v3, v0, 27, 1
	v_lshlrev_b32_e32 v2, 4, v0
	v_lshrrev_b32_e32 v3, 22, v3
	v_add_u32_e32 v3, v2, v3
	v_and_b32_e32 v3, 0xfffffc00, v3
	v_sub_u32_e32 v3, v2, v3
	v_lshrrev_b32_e32 v4, 4, v3
	v_bitop3_b32 v3, v4, v3, 32 bitop3:0x6c
	s_ashr_i32 s43, s42, 31
	s_ashr_i32 s5, s4, 31
	v_ashrrev_i32_e32 v5, 31, v3
	s_add_u32 s28, s8, 0xb900000
	v_readlane_b32 s0, v253, 36
	v_lshrrev_b32_e32 v5, 26, v5
	s_addc_u32 s50, s9, 0
	s_mul_i32 s0, s0, 0x3980000
	v_add_u32_e32 v5, v3, v5
	v_readlane_b32 s1, v253, 37
	s_add_u32 s0, s8, s0
	v_lshlrev_b32_e32 v4, 3, v10
	v_ashrrev_i32_e32 v11, 6, v5
	v_and_b32_e32 v5, 0xc0, v5
	s_addc_u32 s1, s9, 0
	v_and_b32_e32 v4, -16, v4
	v_sub_u32_e32 v3, v3, v5
	s_add_u32 s51, s0, 0x1180000
	v_add_u32_e32 v4, v11, v4
	v_ashrrev_i16_sdwa v3, v232, sext(v3) dst_sel:DWORD dst_unused:UNUSED_PAD src0_sel:DWORD src1_sel:BYTE_0
	s_addc_u32 s52, s1, 0
	v_lshlrev_b32_e32 v6, 5, v10
	v_bfe_i32 v12, v3, 0, 16
	v_lshlrev_b32_e32 v3, 1, v4
	v_lshrrev_b32_e32 v5, 2, v4
	v_and_b32_e32 v7, 3, v11
	s_mov_b32 s1, 0x1fffe0
	v_and_b32_e32 v6, 32, v6
	v_and_b32_e32 v3, 24, v3
	v_and_b32_e32 v5, 4, v5
	v_and_or_b32 v7, v4, s1, v7
	v_or3_b32 v3, v7, v5, v3
	v_add_lshl_u32 v5, v6, v12, 1
	v_add_u32_e32 v2, 0x2000, v2
	v_lshl_add_u32 v132, v3, 11, v5
	v_ashrrev_i32_e32 v3, 31, v2
	v_lshrrev_b32_e32 v3, 22, v3
	v_add_u32_e32 v3, v2, v3
	v_ashrrev_i32_e32 v13, 10, v3
	v_mul_i32_i24_e32 v3, 0x400, v13
	v_sub_u32_e32 v2, v2, v3
	v_lshrrev_b32_e32 v3, 4, v2
	v_bitop3_b32 v2, v3, v2, 32 bitop3:0x6c
	v_lshl_add_u32 v130, v4, 11, v5
	v_ashrrev_i32_e32 v4, 31, v2
	v_lshrrev_b32_e32 v4, 26, v4
	v_lshlrev_b32_e32 v3, 3, v13
	v_add_u32_e32 v4, v2, v4
	v_and_b32_e32 v3, -16, v3
	v_ashrrev_i32_e32 v14, 6, v4
	v_add_u32_e32 v3, v14, v3
	v_and_b32_e32 v6, 3, v14
	v_and_b32_e32 v4, 0xc0, v4
	v_and_or_b32 v6, v3, s1, v6
	s_ashr_i32 s1, s30, 6
	s_ashr_i32 s0, s30, 8
	v_sub_u32_e32 v2, v2, v4
	s_lshl_b32 s53, s1, 10
	s_lshl_b64 s[2:3], s[42:43], 19
	s_lshl_b64 s[18:19], s[4:5], 19
	v_ashrrev_i16_sdwa v2, v232, sext(v2) dst_sel:DWORD dst_unused:UNUSED_PAD src0_sel:DWORD src1_sel:BYTE_0
	s_add_u32 s46, s51, s18
	v_lshlrev_b32_e32 v5, 5, v13
	v_bfe_i32 v15, v2, 0, 16
	v_lshlrev_b32_e32 v2, 1, v3
	v_lshrrev_b32_e32 v4, 2, v3
	s_addc_u32 s47, s52, s19
	s_add_i32 s54, s53, 0
	v_and_b32_e32 v5, 32, v5
	v_and_b32_e32 v2, 24, v2
	v_and_b32_e32 v4, 4, v4
	s_add_i32 m0, s54, 0x10000
	v_or3_b32 v2, v6, v4, v2
	v_add_lshl_u32 v4, v5, v15, 1
	s_waitcnt vmcnt(0) lgkmcnt(0)
	s_barrier
	global_load_lds_dwordx4 v132, s[46:47]
	s_add_i32 m0, s54, 0x12000
	v_lshl_add_u32 v136, v2, 11, v4
	s_add_u32 s18, s46, 0x40000
	global_load_lds_dwordx4 v136, s[46:47]
	s_addc_u32 s19, s47, 0
	s_add_i32 m0, s54, 0x14000
	v_lshl_add_u32 v134, v3, 11, v4
	global_load_lds_dwordx4 v132, s[18:19]
	s_add_i32 m0, s54, 0x16000
	s_add_u32 s44, s28, s2
	s_addc_u32 s45, s50, s3
	s_add_i32 s55, s54, 0x2000
	global_load_lds_dwordx4 v136, s[18:19]
	s_mov_b32 m0, s54
	s_add_u32 s2, s44, 0x40000
	global_load_lds_dwordx4 v130, s[44:45]
	s_mov_b32 m0, s55
	s_addc_u32 s3, s45, 0
	s_add_i32 s56, s54, 0x4000
	global_load_lds_dwordx4 v134, s[44:45]
	s_mov_b32 m0, s56
	s_add_i32 s57, s54, 0x6000
	global_load_lds_dwordx4 v130, s[2:3]
	s_mov_b32 m0, s57
	s_cmp_eq_u32 s0, 1
	global_load_lds_dwordx4 v134, s[2:3]
	v_mov_b32_e32 v133, v1
	v_mov_b32_e32 v137, v1
	v_mov_b32_e32 v131, v1
	v_mov_b32_e32 v135, v1
	s_cselect_b64 s[18:19], -1, 0
	v_lshl_add_u64 v[8:9], s[46:47], 0, v[132:133]
	v_lshl_add_u64 v[6:7], s[46:47], 0, v[136:137]
	v_lshl_add_u64 v[4:5], s[44:45], 0, v[130:131]
	v_lshl_add_u64 v[2:3], s[44:45], 0, v[134:135]
	s_and_b64 vcc, exec, s[18:19]
	s_cbranch_vccz .LBB0_1075
	s_barrier

.LBB0_2723:
	v_readlane_b32 s0, v253, 36
	v_readlane_b32 s1, v253, 37
	s_mul_i32 s28, s0, 0xc3000
	s_ashr_i32 s34, s16, 3
	s_lshl_b64 s[0:1], s[28:29], 2
	s_add_u32 s0, s6, s0
	s_addc_u32 s1, s7, s1
	s_add_u32 s16, s0, 0x43a62400
	s_movk_i32 s0, 0x100
	v_readlane_b32 s18, v254, 24
	s_addc_u32 s17, s1, 0
	s_ashr_i32 s25, s24, 31
	v_cmp_gt_i32_e64 s[0:1], s0, v0
	v_lshl_add_u32 v2, v0, 2, s18
	s_mov_b64 s[18:19], s[4:5]
	s_mov_b32 s100, 0
	s_branch .LBB0_2726

.Lrtc_end:
	s_mov_b64 exec, vcc
	s_add_i32 s0, s31, s34
	s_mul_hi_i32 s1, s0, 0x2e8ba2e9
	s_lshr_b32 s16, s1, 31
	s_ashr_i32 s1, s1, 5
	s_add_i32 s1, s1, s16
	s_lshl_b32 s16, s1, 3
	s_sub_i32 s17, 0x41, s16
	s_min_u32 s17, s17, 8
	s_mulk_i32 s1, 0xb0
	s_sub_i32 s18, s0, s1
	v_cvt_f32_ubyte0_e32 v2, s17
	v_cvt_f32_i32_e32 v0, s18
	v_rcp_iflag_f32_e32 v3, v2
	s_ashr_i32 s0, s18, 30
	s_or_b32 s19, s0, 1
	s_waitcnt lgkmcnt(0)
	v_mul_f32_e32 v3, v0, v3
	v_trunc_f32_e32 v3, v3
	v_fma_f32 v0, -v3, v2, v0
	v_cmp_ge_f32_e64 s[0:1], |v0|, v2
	v_ashrrev_i32_e32 v0, 31, v10
	v_lshrrev_b32_e32 v0, 26, v0
	v_add_u32_e32 v0, v10, v0
	v_ashrrev_i32_e32 v11, 6, v0
	v_bfe_i32 v0, v10, 27, 1
	v_cvt_i32_f32_e32 v3, v3
	v_lshlrev_b32_e32 v2, 4, v10
	v_lshrrev_b32_e32 v0, 22, v0
	v_add_u32_e32 v0, v2, v0
	v_and_b32_e32 v0, 0xfffffc00, v0
	s_and_b64 s[0:1], s[0:1], exec
	v_sub_u32_e32 v0, v2, v0
	v_readfirstlane_b32 s1, v3
	v_lshrrev_b32_e32 v3, 4, v0
	v_bitop3_b32 v0, v3, v0, 32 bitop3:0x6c
	v_ashrrev_i32_e32 v4, 31, v0
	s_cselect_b32 s0, s19, 0
	v_lshrrev_b32_e32 v4, 26, v4
	s_add_i32 s0, s1, s0
	v_add_u32_e32 v4, v0, v4
	s_mul_i32 s1, s0, s17
	v_lshlrev_b32_e32 v3, 3, v11
	v_ashrrev_i32_e32 v12, 6, v4
	v_and_b32_e32 v4, 0xc0, v4
	s_sub_i32 s1, s18, s1
	v_and_b32_e32 v3, -16, v3
	v_sub_u32_e32 v0, v0, v4
	s_sext_i32_i16 s1, s1
	v_add_u32_e32 v3, v12, v3
	v_ashrrev_i16_sdwa v0, v232, sext(v0) dst_sel:DWORD dst_unused:UNUSED_PAD src0_sel:DWORD src1_sel:BYTE_0
	s_add_i32 s38, s16, s1
	s_bfe_i64 s[40:41], s[0:1], 0x100000
	v_lshlrev_b32_e32 v5, 5, v11
	v_bfe_i32 v13, v0, 0, 16
	v_lshlrev_b32_e32 v0, 1, v3
	v_lshrrev_b32_e32 v4, 2, v3
	v_and_b32_e32 v6, 3, v12
	s_mov_b32 s1, 0x1fffe0
	v_and_b32_e32 v5, 32, v5
	v_and_b32_e32 v0, 24, v0
	v_and_b32_e32 v4, 4, v4
	v_and_or_b32 v6, v3, s1, v6
	v_or3_b32 v0, v6, v4, v0
	v_add_lshl_u32 v4, v5, v13, 1
	v_add_u32_e32 v2, 0x2000, v2
	v_lshl_add_u32 v130, v3, 11, v4
	v_ashrrev_i32_e32 v3, 31, v2
	v_lshrrev_b32_e32 v3, 22, v3
	v_add_u32_e32 v3, v2, v3
	v_ashrrev_i32_e32 v14, 10, v3
	v_mul_i32_i24_e32 v3, 0x400, v14
	v_sub_u32_e32 v2, v2, v3
	v_lshrrev_b32_e32 v3, 4, v2
	v_bitop3_b32 v2, v3, v2, 32 bitop3:0x6c
	v_lshl_add_u32 v0, v0, 11, v4
	v_ashrrev_i32_e32 v4, 31, v2
	v_lshrrev_b32_e32 v4, 26, v4
	v_lshlrev_b32_e32 v3, 3, v14
	v_add_u32_e32 v4, v2, v4
	v_and_b32_e32 v3, -16, v3
	v_ashrrev_i32_e32 v15, 6, v4
	v_add_u32_e32 v3, v15, v3
	v_and_b32_e32 v6, 3, v15
	v_and_or_b32 v6, v3, s1, v6
	s_ashr_i32 s1, s30, 6
	s_ashr_i32 s39, s38, 31
	s_ashr_i32 s0, s30, 8
	s_lshl_b32 s28, s1, 10
	s_add_u32 s48, s6, 0xb900000
	v_readlane_b32 s16, v253, 36
	s_addc_u32 s49, s7, 0
	s_mul_i32 s16, s16, 0x3980000
	v_readlane_b32 s17, v253, 37
	s_add_u32 s16, s6, s16
	s_addc_u32 s17, s7, 0
	v_and_b32_e32 v4, 0xc0, v4
	s_add_u32 s50, s16, 0x2a00000
	v_sub_u32_e32 v2, v2, v4
	s_addc_u32 s51, s17, 0
	s_lshl_b64 s[16:17], s[38:39], 19
	s_lshl_b64 s[18:19], s[40:41], 19
	v_ashrrev_i16_sdwa v2, v232, sext(v2) dst_sel:DWORD dst_unused:UNUSED_PAD src0_sel:DWORD src1_sel:BYTE_0
	s_add_u32 s44, s50, s18
	v_lshlrev_b32_e32 v5, 5, v14
	v_bfe_i32 v16, v2, 0, 16
	v_lshlrev_b32_e32 v2, 1, v3
	v_lshrrev_b32_e32 v4, 2, v3
	s_addc_u32 s45, s51, s19
	s_add_i32 s41, s28, 0
	v_and_b32_e32 v5, 32, v5
	v_and_b32_e32 v2, 24, v2
	v_and_b32_e32 v4, 4, v4
	s_add_i32 m0, s41, 0x10000
	v_or3_b32 v2, v6, v4, v2
	v_add_lshl_u32 v4, v5, v16, 1
	s_barrier
	global_load_lds_dwordx4 v0, s[44:45]
	s_add_i32 m0, s41, 0x12000
	v_lshl_add_u32 v134, v2, 11, v4
	s_add_u32 s18, s44, 0x40000
	global_load_lds_dwordx4 v134, s[44:45]
	s_addc_u32 s19, s45, 0
	s_add_i32 m0, s41, 0x14000
	v_lshl_add_u32 v132, v3, 11, v4
	global_load_lds_dwordx4 v0, s[18:19]
	s_add_i32 m0, s41, 0x16000
	s_add_u32 s42, s48, s16
	s_addc_u32 s43, s49, s17
	s_add_i32 s52, s41, 0x2000
	global_load_lds_dwordx4 v134, s[18:19]
	s_mov_b32 m0, s41
	s_add_u32 s16, s42, 0x40000
	global_load_lds_dwordx4 v130, s[42:43]
	s_mov_b32 m0, s52
	s_addc_u32 s17, s43, 0
	s_add_i32 s53, s41, 0x4000
	global_load_lds_dwordx4 v132, s[42:43]
	s_mov_b32 m0, s53
	s_add_i32 s54, s41, 0x6000
	global_load_lds_dwordx4 v130, s[16:17]
	s_mov_b32 m0, s54
	s_cmp_eq_u32 s0, 1
	global_load_lds_dwordx4 v132, s[16:17]
	v_mov_b32_e32 v135, v1
	v_mov_b32_e32 v131, v1
	v_mov_b32_e32 v133, v1
	s_cselect_b64 s[16:17], -1, 0
	v_lshl_add_u64 v[8:9], s[44:45], 0, v[0:1]
	v_lshl_add_u64 v[6:7], s[44:45], 0, v[134:135]
	v_lshl_add_u64 v[4:5], s[42:43], 0, v[130:131]
	v_lshl_add_u64 v[2:3], s[42:43], 0, v[132:133]
	s_and_b64 vcc, exec, s[16:17]
	s_cbranch_vccz .LBB0_2735
	s_barrier

	.amdhsa_kernel _Z6mk_fwd4Args
		.amdhsa_group_segment_fixed_size 0
		.amdhsa_private_segment_fixed_size 0
		.amdhsa_kernarg_size 600
		.amdhsa_user_sgpr_count 2
		.amdhsa_user_sgpr_dispatch_ptr 0
		.amdhsa_user_sgpr_queue_ptr 0
		.amdhsa_user_sgpr_kernarg_segment_ptr 1
		.amdhsa_user_sgpr_dispatch_id 0
		.amdhsa_user_sgpr_kernarg_preload_length 0
		.amdhsa_user_sgpr_kernarg_preload_offset 0
		.amdhsa_user_sgpr_private_segment_size 0
		.amdhsa_uses_dynamic_stack 0
		.amdhsa_enable_private_segment 0
		.amdhsa_system_sgpr_workgroup_id_x 1
		.amdhsa_system_sgpr_workgroup_id_y 0
		.amdhsa_system_sgpr_workgroup_id_z 0
		.amdhsa_system_sgpr_workgroup_info 0
		.amdhsa_system_vgpr_workitem_id 0
		.amdhsa_next_free_vgpr 256
		.amdhsa_next_free_sgpr 102
		.amdhsa_accum_offset 256
		.amdhsa_reserve_vcc 1
		.amdhsa_float_round_mode_32 0
		.amdhsa_float_round_mode_16_64 0
		.amdhsa_float_denorm_mode_32 3
		.amdhsa_float_denorm_mode_16_64 3
		.amdhsa_dx10_clamp 1
		.amdhsa_ieee_mode 1
		.amdhsa_fp16_overflow 0
		.amdhsa_tg_split 0
		.amdhsa_exception_fp_ieee_invalid_op 0
		.amdhsa_exception_fp_denorm_src 0
		.amdhsa_exception_fp_ieee_div_zero 0
		.amdhsa_exception_fp_ieee_overflow 0
		.amdhsa_exception_fp_ieee_underflow 0
		.amdhsa_exception_fp_ieee_inexact 0
		.amdhsa_exception_int_div_zero 0
	.end_amdhsa_kernel

amdhsa.kernels:
  - .agpr_count:     0
    .args:
      - .offset:         0
        .size:           344
        .value_kind:     by_value
      - .offset:         344
        .size:           4
        .value_kind:     hidden_block_count_x
      - .offset:         348
        .size:           4
        .value_kind:     hidden_block_count_y
      - .offset:         352
        .size:           4
        .value_kind:     hidden_block_count_z
      - .offset:         356
        .size:           2
        .value_kind:     hidden_group_size_x
      - .offset:         358
        .size:           2
        .value_kind:     hidden_group_size_y
      - .offset:         360
        .size:           2
        .value_kind:     hidden_group_size_z
      - .offset:         362
        .size:           2
        .value_kind:     hidden_remainder_x
      - .offset:         364
        .size:           2
        .value_kind:     hidden_remainder_y
      - .offset:         366
        .size:           2
        .value_kind:     hidden_remainder_z
      - .offset:         384
        .size:           8
        .value_kind:     hidden_global_offset_x
      - .offset:         392
        .size:           8
        .value_kind:     hidden_global_offset_y
      - .offset:         400
        .size:           8
        .value_kind:     hidden_global_offset_z
      - .offset:         408
        .size:           2
        .value_kind:     hidden_grid_dims
      - .offset:         464
        .size:           4
        .value_kind:     hidden_dynamic_lds_size
    .group_segment_fixed_size: 0
    .kernarg_segment_align: 8
    .kernarg_segment_size: 600
    .language:       OpenCL C
    .language_version:
      - 2
      - 0
    .max_flat_workgroup_size: 512
    .name:           _Z6mk_fwd4Args
    .private_segment_fixed_size: 0
    .sgpr_count:     108
    .sgpr_spill_count: 209
    .symbol:         _Z6mk_fwd4Args.kd
    .uniform_work_group_size: 1
    .uses_dynamic_stack: false
    .vgpr_count:     256
    .vgpr_spill_count: 0
    .wavefront_size: 64
